# group barriers extended to seam 4 (hy_transpose items panel-local, global P4-done counter guards FFN-up's aliased HID writes); stagger moved to GLU phase start
# speedup vs baseline: 1.0209x; 1.0025x over previous
.LBB0_914:
	s_cmp_lt_i32 s24, 5
	s_cselect_b64 s[6:7], -1, 0
	s_and_b64 s[0:1], s[6:7], s[0:1]
	s_andn2_b64 vcc, exec, s[0:1]
	s_cbranch_vccnz .LBB0_943
	s_add_u32 s8, s22, 0x1be4c100
	s_addc_u32 s9, s23, 0
	v_and_b32_e32 v0, 63, v144
	global_load_ubyte v1, v0, s[8:9] sc1
	global_load_ubyte v2, v0, s[8:9] offset:64 sc1
	global_load_ubyte v3, v0, s[8:9] offset:128 sc1
	global_load_ubyte v4, v0, s[8:9] offset:192 sc1
	s_waitcnt vmcnt(0)
	v_cmp_eq_u32_e32 vcc, v1, v2
	v_cmp_eq_u32_e64 s[10:11], v1, v3
	v_cmp_eq_u32_e64 s[12:13], v1, v4
	s_nop 3
	s_and_b64 s[10:11], s[10:11], s[12:13]
	s_and_b64 vcc, vcc, s[10:11]
	s_cmp_eq_u64 vcc, exec
	s_cselect_b32 s32, 1, 0
	s_cmp_eq_u32 s32, 0
	s_cbranch_scc1 .Lstag_done
	s_and_b32 s98, s3, 3
	s_cmp_eq_u32 s98, 0
	s_cbranch_scc1 .Lstag_done

.Lstag_done:
	v_readfirstlane_b32 s2, v144
	s_cmpk_gt_i32 s3, 0x1ff
	v_lshrrev_b32_e32 v145, 2, v144
	s_cbranch_scc1 .LBB0_938
	s_ashr_i32 s33, s3, 31
	s_lshr_b32 s6, s33, 29
	s_add_i32 s8, s3, s6
	s_and_b32 s6, s8, -8
	s_sub_i32 s10, s3, s6
	s_cmp_gt_i32 s10, -1
	s_cbranch_scc0 .LBB0_918
	s_lshl_b32 s9, s10, 6
	s_cbranch_execz .LBB0_919
	s_branch .LBB0_920

.LBB0_938:
	s_cmpk_gt_i32 s3, 0xff
	s_cbranch_scc1 .LBB0_943
	s_waitcnt vmcnt(0)
	v_mbcnt_lo_u32_b32 v1, -1, 0
	v_mbcnt_hi_u32_b32 v1, -1, v1
	v_and_b32_e32 v2, 64, v1
	v_add_u32_e32 v2, 64, v2
	v_xor_b32_e32 v3, 32, v1
	v_cmp_lt_i32_e32 vcc, v3, v2
	v_lshlrev_b32_e32 v0, 3, v144
	v_lshrrev_b32_e32 v7, 6, v144
	v_cndmask_b32_e32 v3, v1, v3, vcc
	v_lshlrev_b32_e32 v8, 2, v3
	v_xor_b32_e32 v3, 16, v1
	v_cmp_lt_i32_e32 vcc, v3, v2
	v_and_b32_e32 v0, 56, v0
	v_mul_u32_u24_e32 v5, 0x804, v0
	v_cndmask_b32_e32 v3, v1, v3, vcc
	v_lshlrev_b32_e32 v9, 2, v3
	v_xor_b32_e32 v3, 8, v1
	v_cmp_lt_i32_e32 vcc, v3, v2
	v_lshlrev_b32_e32 v0, 1, v0
	v_and_b32_e32 v4, 63, v144
	v_cndmask_b32_e32 v3, v1, v3, vcc
	v_lshlrev_b32_e32 v10, 2, v3
	v_xor_b32_e32 v3, 4, v1
	v_cmp_lt_i32_e32 vcc, v3, v2
	s_waitcnt lgkmcnt(0)
	v_readlane_b32 s36, v248, 24
	v_readlane_b32 s46, v248, 34
	v_cndmask_b32_e32 v3, v1, v3, vcc
	v_lshlrev_b32_e32 v11, 2, v3
	v_xor_b32_e32 v3, 2, v1
	v_cmp_lt_i32_e32 vcc, v3, v2
	v_readlane_b32 s47, v248, 35
	v_lshlrev_b32_e32 v15, 3, v7
	v_cndmask_b32_e32 v3, v1, v3, vcc
	v_lshlrev_b32_e32 v12, 2, v3
	v_xor_b32_e32 v3, 1, v1
	v_cmp_lt_i32_e32 vcc, v3, v2
	v_and_b32_e32 v2, 14, v145
	v_lshlrev_b32_e32 v16, 5, v4
	v_cndmask_b32_e32 v1, v1, v3, vcc
	v_lshlrev_b32_e32 v13, 2, v1
	v_mov_b32_e32 v1, 0
	v_lshl_add_u32 v3, v7, 4, 0
	v_add3_u32 v14, v3, v2, v5
	v_lshl_add_u64 v[2:3], s[22:23], 0, v[0:1]
	v_lshlrev_b32_e32 v0, 12, v144
	v_and_b32_e32 v0, 0x38000, v0
	v_lshl_or_b32 v0, v7, 18, v0
	v_lshl_add_u64 v[2:3], v[2:3], 0, v[0:1]
	v_lshlrev_b32_e32 v0, 6, v4
	v_lshlrev_b32_e32 v6, 4, v4
	s_mov_b64 s[6:7], 0x12a00000
	v_lshl_add_u64 v[4:5], s[46:47], 0, v[0:1]
	v_mul_u32_u24_e32 v0, 0x4020, v7
	v_lshl_add_u64 v[2:3], v[2:3], 0, s[6:7]
	s_and_b32 s98, s3, 7
	s_lshl_b32 s98, s98, 5
	s_bfe_u32 s99, s3, 0x30003
	s_lshl_b32 s99, s99, 2
	s_or_b32 s98, s98, s99
	s_lshr_b32 s99, s3, 6
	s_or_b32 s98, s98, s99
	v_lshl_add_u32 v15, s98, 6, v15
	s_lshl_b32 s2, s26, 6
	v_add3_u32 v16, v0, v16, 0
	s_mov_b32 s8, 0x800000
	v_mov_b32_e32 v17, 0x358637bd
	v_lshlrev_b32_e32 v0, 1, v6
	s_mov_b64 s[6:7], 0x5e00800
	s_mov_b32 s9, s98
	v_readlane_b32 s37, v248, 25
	v_readlane_b32 s38, v248, 26
	v_readlane_b32 s39, v248, 27
	v_readlane_b32 s40, v248, 28
	v_readlane_b32 s41, v248, 29
	v_readlane_b32 s42, v248, 30
	v_readlane_b32 s43, v248, 31
	v_readlane_b32 s44, v248, 32
	v_readlane_b32 s45, v248, 33
	v_readlane_b32 s48, v248, 36
	v_readlane_b32 s49, v248, 37
	v_readlane_b32 s50, v248, 38
	v_readlane_b32 s51, v248, 39
	global_load_dwordx4 v[180:183], v[4:5], off
	global_load_dwordx4 v[184:187], v[4:5], off offset:16
	global_load_dwordx4 v[188:191], v[4:5], off offset:32
	global_load_dwordx4 v[192:195], v[4:5], off offset:48

.LBB0_943:
	s_cmp_gt_i32 s25, 5
	s_cselect_b64 s[6:7], -1, 0
	s_and_b64 s[0:1], s[0:1], s[6:7]
	s_andn2_b64 vcc, exec, s[0:1]
	s_cbranch_vccnz .LBB0_997
	s_cmp_lg_u32 s32, 0
	s_addc_u32 s32, s32, 0
	s_waitcnt vmcnt(0)
	s_waitcnt vmcnt(0) lgkmcnt(0)
	s_barrier
	s_and_saveexec_b64 s[0:1], s[4:5]
	s_cbranch_execz .LBB0_996
	s_cmp_lg_u32 s32, 0
	s_cbranch_scc1 .Lgb4
	s_add_i32 s2, 0, 0x23fe0
	v_mov_b32_e32 v0, s2
	s_waitcnt vmcnt(0) expcnt(0) lgkmcnt(0)
	ds_read_b32 v2, v0
	s_add_i32 s2, 0, 0x23fe4
	v_mov_b32_e32 v0, s2
	ds_read_b32 v0, v0
	s_waitcnt lgkmcnt(1)
	v_cmp_ne_u32_e32 vcc, 0, v2
	s_cbranch_vccnz .LBB0_960
	s_add_u32 s8, s22, 0x1be4c300
	s_addc_u32 s9, s23, 0
	s_add_u32 s10, s22, 0x1be4c500
	s_addc_u32 s11, s23, 0
	s_add_u32 s12, s22, 0x1be4c600
	s_addc_u32 s13, s23, 0
	s_add_u32 s14, s22, 0x1be4c700
	s_addc_u32 s15, s23, 0
	s_add_u32 s16, s22, 0x1be4c800
	s_addc_u32 s17, s23, 0
	s_add_u32 s18, s22, 0x1be4c900
	s_addc_u32 s19, s23, 0
	s_add_u32 s30, s22, 0x1be4ca00
	s_addc_u32 s31, s23, 0
	s_add_u32 s34, s22, 0x1be4cb00
	s_addc_u32 s35, s23, 0
	s_add_u32 s36, s22, 0x1be4cc00
	s_addc_u32 s37, s23, 0
	s_add_u32 s38, s22, 0x1be4cd00
	s_addc_u32 s39, s23, 0
	s_add_u32 s40, s22, 0x1be4ce00
	s_addc_u32 s41, s23, 0
	s_add_u32 s42, s22, 0x1be4cf00
	s_addc_u32 s43, s23, 0
	s_add_u32 s44, s22, 0x1be4d000
	s_addc_u32 s45, s23, 0
	s_add_u32 s46, s22, 0x1be4d100
	s_addc_u32 s47, s23, 0
	s_add_u32 s48, s22, 0x1be4d200
	s_addc_u32 s49, s23, 0
	s_add_u32 s50, s22, 0x1be4d300
	s_addc_u32 s51, s23, 0
	s_mul_i32 s2, s27, s97
	s_add_u32 s54, s22, 0x1be4d400
	s_mul_i32 s2, s2, s26
	s_addc_u32 s55, s23, 0
	s_mov_b32 s33, 1
	v_mov_b32_e32 v16, 0
	s_branch .LBB0_948

.Lgb4_poll:
	global_load_dword v2, v0, s[8:9] sc1
	s_add_i32 s10, s10, 1
	s_waitcnt vmcnt(0)
	v_cmp_gt_u32_e32 vcc, s2, v2
	s_cmp_lt_u32 s10, 0x4000
	s_cselect_b64 s[12:13], -1, 0
	s_and_b64 vcc, vcc, s[12:13]
	s_cbranch_vccnz .Lgb4_poll
	s_add_u32 s12, s22, 0x1be4c400
	s_addc_u32 s13, s23, 0
	global_atomic_add v0, v1, s[12:13]
	buffer_inv sc1
	s_waitcnt vmcnt(0)

.LBB0_997:
	s_cmp_lt_i32 s24, 6
	s_cselect_b64 s[0:1], -1, 0
	s_and_b64 s[6:7], s[0:1], s[6:7]
	s_andn2_b64 vcc, exec, s[6:7]
	v_lshrrev_b32_e32 v145, 4, v144
	s_cbranch_vccnz .LBB0_1002
	s_waitcnt vmcnt(0)
	v_and_b32_e32 v0, 60, v145
	s_and_b32 s98, s3, 7
	s_lshl_b32 s98, s98, 11
	s_bfe_u32 s99, s3, 0x30003
	s_lshl_b32 s99, s99, 8
	s_or_b32 s98, s98, s99
	s_lshr_b32 s99, s3, 6
	s_lshl_b32 s99, s99, 6
	s_or_b32 s98, s98, s99
	v_add_u32_e32 v0, s98, v0
	s_movk_i32 s0, 0x4000
	v_cmp_gt_i32_e32 vcc, s0, v0
	s_and_saveexec_b64 s[8:9], vcc
	s_cbranch_execz .LBB0_1001
	v_lshlrev_b32_e32 v1, 4, v144
	v_and_b32_e32 v1, 0x3f0, v1
	s_waitcnt lgkmcnt(0)
	v_readlane_b32 s36, v248, 24
	v_lshlrev_b32_e32 v4, 2, v1
	v_mov_b32_e32 v5, 0
	v_readlane_b32 s44, v248, 32
	v_readlane_b32 s45, v248, 33
	s_mov_b64 s[0:1], 0x5e00000
	s_lshl_b32 s2, s26, 5
	v_lshl_add_u64 v[2:3], s[44:45], 0, v[4:5]
	v_lshlrev_b32_e32 v4, 1, v1
	v_mbcnt_lo_u32_b32 v1, -1, 0
	v_mbcnt_hi_u32_b32 v1, -1, v1
	v_and_b32_e32 v6, 64, v1
	v_add_u32_e32 v6, 64, v6
	v_xor_b32_e32 v7, 32, v1
	v_cmp_lt_i32_e32 vcc, v7, v6
	v_lshl_add_u64 v[4:5], s[22:23], 0, v[4:5]
	v_lshl_add_u64 v[4:5], v[4:5], 0, s[0:1]
	v_cndmask_b32_e32 v7, v1, v7, vcc
	v_lshlrev_b32_e32 v30, 2, v7
	v_xor_b32_e32 v7, 16, v1
	v_cmp_lt_i32_e32 vcc, v7, v6
	s_mov_b32 s0, 0x358637bd
	s_mov_b64 s[10:11], 0
	v_cndmask_b32_e32 v7, v1, v7, vcc
	v_lshlrev_b32_e32 v31, 2, v7
	v_xor_b32_e32 v7, 8, v1
	v_cmp_lt_i32_e32 vcc, v7, v6
	s_mov_b32 s12, 0x3a800000
	s_mov_b32 s13, 0x800000
	v_cndmask_b32_e32 v7, v1, v7, vcc
	v_lshlrev_b32_e32 v32, 2, v7
	v_xor_b32_e32 v7, 4, v1
	v_cmp_lt_i32_e32 vcc, v7, v6
	s_movk_i32 s14, 0x3fff
	v_readlane_b32 s37, v248, 25
	v_cndmask_b32_e32 v7, v1, v7, vcc
	v_lshlrev_b32_e32 v33, 2, v7
	v_xor_b32_e32 v7, 2, v1
	v_cmp_lt_i32_e32 vcc, v7, v6
	v_readlane_b32 s38, v248, 26
	v_readlane_b32 s39, v248, 27
	v_cndmask_b32_e32 v7, v1, v7, vcc
	v_lshlrev_b32_e32 v34, 2, v7
	v_xor_b32_e32 v7, 1, v1
	v_cmp_lt_i32_e32 vcc, v7, v6
	v_readlane_b32 s40, v248, 28
	v_readlane_b32 s41, v248, 29
	v_cndmask_b32_e32 v1, v1, v7, vcc
	v_lshlrev_b32_e32 v35, 2, v1
	v_mov_b64_e32 v[6:7], s[0:1]
	v_readlane_b32 s42, v248, 30
	v_readlane_b32 s43, v248, 31
	v_readlane_b32 s46, v248, 34
	v_readlane_b32 s47, v248, 35
	v_readlane_b32 s48, v248, 36
	v_readlane_b32 s49, v248, 37
	v_readlane_b32 s50, v248, 38
	v_readlane_b32 s51, v248, 39
	global_load_dwordx4 v[180:183], v[2:3], off
	global_load_dwordx4 v[184:187], v[2:3], off offset:16
	global_load_dwordx4 v[188:191], v[2:3], off offset:32
	global_load_dwordx4 v[192:195], v[2:3], off offset:48

.Lgb7_poll:
	global_load_dword v2, v0, s[8:9] sc1
	s_add_i32 s10, s10, 1
	s_waitcnt vmcnt(0)
	v_cmp_gt_u32_e32 vcc, s2, v2
	s_cmp_lt_u32 s10, 0x4000
	s_cselect_b64 s[12:13], -1, 0
	s_and_b64 vcc, vcc, s[12:13]
	s_cbranch_vccnz .Lgb7_poll
	s_add_u32 s12, s22, 0x1be4c400
	s_addc_u32 s13, s23, 0
	s_mov_b32 s10, 0
.Lp4done_poll:
	global_load_dword v2, v0, s[12:13] sc1
	s_add_i32 s10, s10, 1
	s_waitcnt vmcnt(0)
	v_cmp_gt_u32_e32 vcc, 0x100, v2
	s_cmp_lt_u32 s10, 0x4000
	s_cselect_b64 s[14:15], -1, 0
	s_and_b64 vcc, vcc, s[14:15]
	s_cbranch_vccnz .Lp4done_poll
	buffer_inv sc1
	s_waitcnt vmcnt(0)
